# attention epilogue sub-LN row reductions: xor-1/2/4/8 butterfly steps done with DPP adds instead of ds_bpermute round trips (same partner sums); lgkmcnt waits recomputed
# speedup vs baseline: 1.0017x; 1.0017x over previous
.LBB0_658:
	s_waitcnt vmcnt(0) lgkmcnt(0)
	s_barrier
	s_andn2_b64 vcc, exec, s[46:47]
	s_cbranch_vccnz .LBB0_660
	v_add_u32_e32 v168, 0x400, v166
	v_add_u32_e32 v169, 0x1000, v166
	v_add_u32_e32 v170, 0x1400, v166
	v_add_u32_e32 v171, 0x2000, v166
	v_add_u32_e32 v172, 0x2400, v166
	v_add_u32_e32 v173, 0x3000, v166
	v_add_u32_e32 v174, 0x3400, v166
	ds_read2_b32 v[98:99], v166 offset1:32
	ds_read2_b32 v[100:101], v166 offset0:128 offset1:160
	ds_read2_b32 v[102:103], v168 offset1:32
	ds_read2_b32 v[104:105], v168 offset0:128 offset1:160
	ds_read2_b32 v[106:107], v169 offset1:32
	ds_read2_b32 v[108:109], v169 offset0:128 offset1:160
	ds_read2_b32 v[110:111], v170 offset1:32
	ds_read2_b32 v[116:117], v170 offset0:128 offset1:160
	ds_read2_b32 v[118:119], v171 offset1:32
	ds_read2_b32 v[176:177], v171 offset0:128 offset1:160
	ds_read2_b32 v[178:179], v172 offset1:32
	ds_read2_b32 v[180:181], v172 offset0:128 offset1:160
	ds_read2_b32 v[182:183], v173 offset1:32
	ds_read2_b32 v[184:185], v173 offset0:128 offset1:160
	ds_read2_b32 v[186:187], v174 offset1:32
	ds_read2_b32 v[188:189], v174 offset0:128 offset1:160
	v_mov_b32_e32 v124, v64
	v_mov_b32_e32 v125, v48
	v_mov_b32_e32 v48, v65
	v_mov_b32_e32 v64, v66
	v_mov_b32_e32 v65, v50
	v_mov_b32_e32 v50, v67
	v_mov_b32_e32 v66, v68
	v_mov_b32_e32 v67, v52
	v_mov_b32_e32 v52, v69
	v_mov_b32_e32 v68, v70
	v_mov_b32_e32 v69, v54
	v_mov_b32_e32 v54, v71
	v_mov_b32_e32 v70, v72
	v_mov_b32_e32 v71, v56
	v_mov_b32_e32 v56, v73
	v_mov_b32_e32 v72, v74
	v_mov_b32_e32 v73, v58
	v_mov_b32_e32 v58, v75
	v_mov_b32_e32 v74, v76
	v_mov_b32_e32 v75, v60
	v_mov_b32_e32 v60, v77
	v_mov_b32_e32 v76, v78
	v_mov_b32_e32 v77, v62
	v_mov_b32_e32 v62, v79
	s_waitcnt lgkmcnt(14)
	v_pk_fma_f32 v[98:99], v[124:125], v[154:155], v[98:99] op_sel_hi:[1,0,1] neg_lo:[0,0,1] neg_hi:[0,0,1]
	v_pk_fma_f32 v[48:49], v[48:49], v[150:151], v[100:101] op_sel_hi:[1,0,1] neg_lo:[0,0,1] neg_hi:[0,0,1]
	s_waitcnt lgkmcnt(6)
	v_pk_fma_f32 v[56:57], v[56:57], v[134:135], v[176:177] op_sel_hi:[1,0,1] neg_lo:[0,0,1] neg_hi:[0,0,1]
	s_waitcnt lgkmcnt(5)
	v_pk_fma_f32 v[72:73], v[72:73], v[130:131], v[178:179] op_sel_hi:[1,0,1] neg_lo:[0,0,1] neg_hi:[0,0,1]
	s_waitcnt lgkmcnt(4)
	v_pk_fma_f32 v[58:59], v[58:59], v[128:129], v[180:181] op_sel_hi:[1,0,1] neg_lo:[0,0,1] neg_hi:[0,0,1]
	s_waitcnt lgkmcnt(3)
	v_pk_fma_f32 v[74:75], v[74:75], v[122:123], v[182:183] op_sel_hi:[1,0,1] neg_lo:[0,0,1] neg_hi:[0,0,1]
	s_waitcnt lgkmcnt(2)
	v_pk_fma_f32 v[60:61], v[60:61], v[120:121], v[184:185] op_sel_hi:[1,0,1] neg_lo:[0,0,1] neg_hi:[0,0,1]
	s_waitcnt lgkmcnt(1)
	v_pk_fma_f32 v[76:77], v[76:77], v[112:113], v[186:187] op_sel_hi:[1,0,1] neg_lo:[0,0,1] neg_hi:[0,0,1]
	s_waitcnt lgkmcnt(0)
	v_pk_fma_f32 v[62:63], v[62:63], v[114:115], v[188:189] op_sel_hi:[1,0,1] neg_lo:[0,0,1] neg_hi:[0,0,1]
	ds_read2_b32 v[78:79], v166 offset0:64 offset1:96
	ds_read2_b32 v[176:177], v166 offset0:192 offset1:224
	ds_read2_b32 v[178:179], v168 offset0:64 offset1:96
	ds_read2_b32 v[180:181], v168 offset0:192 offset1:224
	ds_read2_b32 v[182:183], v169 offset0:64 offset1:96
	ds_read2_b32 v[184:185], v169 offset0:192 offset1:224
	ds_read2_b32 v[186:187], v170 offset0:64 offset1:96
	ds_read2_b32 v[188:189], v170 offset0:192 offset1:224
	ds_read2_b32 v[190:191], v171 offset0:64 offset1:96
	ds_read2_b32 v[192:193], v171 offset0:192 offset1:224
	ds_read2_b32 v[194:195], v172 offset0:64 offset1:96
	ds_read2_b32 v[196:197], v172 offset0:192 offset1:224
	ds_read2_b32 v[198:199], v173 offset0:64 offset1:96
	ds_read2_b32 v[200:201], v173 offset0:192 offset1:224
	ds_read2_b32 v[202:203], v174 offset0:64 offset1:96
	ds_read2_b32 v[204:205], v174 offset0:192 offset1:224
	v_mov_b32_e32 v206, v32
	v_mov_b32_e32 v207, v16
	v_mov_b32_e32 v16, v33
	v_pk_mul_f32 v[162:163], v[98:99], v[98:99]
	v_pk_mul_f32 v[164:165], v[48:49], v[48:49]
	s_waitcnt lgkmcnt(14)
	v_pk_fma_f32 v[78:79], v[206:207], v[154:155], v[78:79] op_sel_hi:[1,0,1] neg_lo:[0,0,1] neg_hi:[0,0,1]
	v_pk_fma_f32 v[16:17], v[16:17], v[150:151], v[176:177] op_sel_hi:[1,0,1] neg_lo:[0,0,1] neg_hi:[0,0,1]
	v_mov_b32_e32 v32, v34
	v_mov_b32_e32 v33, v18
	v_mov_b32_e32 v18, v35
	v_mov_b32_e32 v34, v36
	v_mov_b32_e32 v35, v20
	v_mov_b32_e32 v20, v37
	v_mov_b32_e32 v36, v38
	v_mov_b32_e32 v37, v22
	v_pk_mul_f32 v[206:207], v[78:79], v[78:79]
	v_pk_mul_f32 v[176:177], v[16:17], v[16:17]
	s_waitcnt lgkmcnt(9)
	v_pk_fma_f32 v[36:37], v[36:37], v[136:137], v[186:187] op_sel_hi:[1,0,1] neg_lo:[0,0,1] neg_hi:[0,0,1]
	v_mov_b32_e32 v186, v164
	v_mov_b32_e32 v187, v162
	v_mov_b32_e32 v162, v165
	v_pk_add_f32 v[162:163], v[186:187], v[162:163]
	v_mov_b32_e32 v164, v176
	v_mov_b32_e32 v165, v206
	v_pk_add_f32 v[162:163], v[162:163], v[164:165]
	v_mov_b32_e32 v206, v177
	v_xor_b32_e32 v175, 4, v115
	v_pk_add_f32 v[162:163], v[162:163], v[206:207]
	v_pk_fma_f32 v[64:65], v[64:65], v[148:149], v[102:103] op_sel_hi:[1,0,1] neg_lo:[0,0,1] neg_hi:[0,0,1]
	v_pk_fma_f32 v[32:33], v[32:33], v[148:149], v[178:179] op_sel_hi:[1,0,1] neg_lo:[0,0,1] neg_hi:[0,0,1]
	v_xor_b32_e32 v148, 8, v115
	v_xor_b32_e32 v150, 16, v115
	s_waitcnt lgkmcnt(0)
	s_nop 1
	v_add_f32_dpp v162, v162, v162 quad_perm:[1,0,3,2] row_mask:0xf bank_mask:0xf
	v_add_f32_dpp v163, v163, v163 quad_perm:[1,0,3,2] row_mask:0xf bank_mask:0xf
	v_pk_fma_f32 v[50:51], v[50:51], v[146:147], v[104:105] op_sel_hi:[1,0,1] neg_lo:[0,0,1] neg_hi:[0,0,1]
	v_pk_mul_f32 v[158:159], v[64:65], v[64:65]
	v_pk_mul_f32 v[160:161], v[50:51], v[50:51]
	v_pk_fma_f32 v[18:19], v[18:19], v[146:147], v[180:181] op_sel_hi:[1,0,1] neg_lo:[0,0,1] neg_hi:[0,0,1]
	s_waitcnt lgkmcnt(0)
	s_nop 1
	v_add_f32_dpp v162, v162, v162 quad_perm:[2,3,0,1] row_mask:0xf bank_mask:0xf
	v_add_f32_dpp v163, v163, v163 quad_perm:[2,3,0,1] row_mask:0xf bank_mask:0xf
	v_mov_b32_e32 v22, v39
	v_mov_b32_e32 v39, v24
	v_mov_b32_e32 v24, v41
	v_mov_b32_e32 v41, v26
	v_mov_b32_e32 v26, v43
	v_mov_b32_e32 v43, v28
	v_mov_b32_e32 v28, v45
	v_mov_b32_e32 v45, v30
	v_mov_b32_e32 v30, v47
	v_pk_mul_f32 v[178:179], v[32:33], v[32:33]
	v_pk_mul_f32 v[180:181], v[18:19], v[18:19]
	v_xor_b32_e32 v154, 32, v115
	s_waitcnt lgkmcnt(0)
	s_nop 1
	v_add_f32_dpp v164, v162, v162 row_half_mirror row_mask:0xf bank_mask:0xf
	v_add_f32_dpp v165, v163, v163 row_half_mirror row_mask:0xf bank_mask:0xf
	v_pk_fma_f32 v[30:31], v[30:31], v[114:115], v[204:205] op_sel_hi:[1,0,1] neg_lo:[0,0,1] neg_hi:[0,0,1]
	v_xor_b32_e32 v162, 64, v115
	v_mov_b32_e32 v114, v160
	v_mov_b32_e32 v115, v158
	v_mov_b32_e32 v158, v161
	v_pk_add_f32 v[114:115], v[114:115], v[158:159]
	v_mov_b32_e32 v158, v180
	v_mov_b32_e32 v159, v178
	v_pk_add_f32 v[114:115], v[114:115], v[158:159]
	v_mov_b32_e32 v178, v181
	v_pk_add_f32 v[158:159], v[114:115], v[178:179]
	v_mov_b32_e32 v38, v40
	v_mov_b32_e32 v40, v42
	s_waitcnt lgkmcnt(0)
	s_nop 1
	v_add_f32_dpp v158, v158, v158 quad_perm:[1,0,3,2] row_mask:0xf bank_mask:0xf
	v_add_f32_dpp v159, v159, v159 quad_perm:[1,0,3,2] row_mask:0xf bank_mask:0xf
	v_mov_b32_e32 v42, v44
	v_mov_b32_e32 v44, v46
	s_waitcnt lgkmcnt(0)
	s_nop 1
	v_add_f32_dpp v46, v164, v164 row_mirror row_mask:0xf bank_mask:0xf
	v_add_f32_dpp v47, v165, v165 row_mirror row_mask:0xf bank_mask:0xf
	ds_bpermute_b32 v165, v162, v47
	ds_bpermute_b32 v164, v162, v46
	s_waitcnt lgkmcnt(2)
	s_nop 1
	v_add_f32_dpp v158, v158, v158 quad_perm:[2,3,0,1] row_mask:0xf bank_mask:0xf
	v_add_f32_dpp v159, v159, v159 quad_perm:[2,3,0,1] row_mask:0xf bank_mask:0xf
	s_mov_b32 s4, 0x358637bd
	s_waitcnt lgkmcnt(0)
	v_pk_add_f32 v[164:165], v[46:47], v[164:165]
	v_mov_b64_e32 v[46:47], s[4:5]
	v_pk_fma_f32 v[66:67], v[66:67], v[140:141], v[106:107] op_sel_hi:[1,0,1] neg_lo:[0,0,1] neg_hi:[0,0,1]
	v_pk_fma_f32 v[52:53], v[52:53], v[142:143], v[108:109] op_sel_hi:[1,0,1] neg_lo:[0,0,1] neg_hi:[0,0,1]
	v_pk_fma_f32 v[164:165], v[164:165], s[50:51], v[46:47] op_sel_hi:[1,0,0]
	v_pk_mul_f32 v[152:153], v[66:67], v[66:67]
	v_pk_mul_f32 v[156:157], v[52:53], v[52:53]
	v_pk_fma_f32 v[70:71], v[70:71], v[138:139], v[118:119] op_sel_hi:[1,0,1] neg_lo:[0,0,1] neg_hi:[0,0,1]
	v_pk_fma_f32 v[34:35], v[34:35], v[140:141], v[182:183] op_sel_hi:[1,0,1] neg_lo:[0,0,1] neg_hi:[0,0,1]
	v_pk_fma_f32 v[20:21], v[20:21], v[142:143], v[184:185] op_sel_hi:[1,0,1] neg_lo:[0,0,1] neg_hi:[0,0,1]
	v_pk_fma_f32 v[38:39], v[38:39], v[138:139], v[190:191] op_sel_hi:[1,0,1] neg_lo:[0,0,1] neg_hi:[0,0,1]
	v_mul_f32_e32 v138, 0x4b800000, v165
	v_cmp_gt_f32_e32 vcc, s94, v165
	v_mul_f32_e32 v142, 0x4b800000, v164
	v_cmp_gt_f32_e64 s[4:5], s94, v164
	v_pk_mul_f32 v[182:183], v[34:35], v[34:35]
	v_pk_mul_f32 v[184:185], v[20:21], v[20:21]
	v_cndmask_b32_e32 v138, v165, v138, vcc
	v_cndmask_b32_e64 v142, v164, v142, s[4:5]
	v_mov_b32_e32 v164, v156
	v_mov_b32_e32 v165, v152
	v_mov_b32_e32 v152, v157
	s_waitcnt lgkmcnt(0)
	s_nop 1
	v_add_f32_dpp v158, v158, v158 row_half_mirror row_mask:0xf bank_mask:0xf
	v_add_f32_dpp v159, v159, v159 row_half_mirror row_mask:0xf bank_mask:0xf
	v_pk_add_f32 v[152:153], v[164:165], v[152:153]
	v_mov_b32_e32 v156, v184
	v_mov_b32_e32 v157, v182
	v_pk_add_f32 v[152:153], v[152:153], v[156:157]
	v_mov_b32_e32 v182, v185
	v_pk_add_f32 v[152:153], v[152:153], v[182:183]
	s_waitcnt lgkmcnt(0)
	s_nop 1
	v_add_f32_dpp v158, v158, v158 row_mirror row_mask:0xf bank_mask:0xf
	v_add_f32_dpp v159, v159, v159 row_mirror row_mask:0xf bank_mask:0xf
	ds_bpermute_b32 v161, v162, v159
	ds_bpermute_b32 v160, v162, v158
	v_rsq_f32_e32 v138, v138
	s_waitcnt lgkmcnt(2)
	s_nop 1
	v_add_f32_dpp v152, v152, v152 quad_perm:[1,0,3,2] row_mask:0xf bank_mask:0xf
	v_add_f32_dpp v153, v153, v153 quad_perm:[1,0,3,2] row_mask:0xf bank_mask:0xf
	v_rsq_f32_e32 v142, v142
	v_mul_f32_e32 v146, 0x45800000, v138
	s_waitcnt lgkmcnt(0)
	v_pk_add_f32 v[158:159], v[158:159], v[160:161]
	v_cndmask_b32_e32 v138, v138, v146, vcc
	v_mul_f32_e32 v146, 0x45800000, v142
	v_pk_fma_f32 v[158:159], v[158:159], s[50:51], v[46:47] op_sel_hi:[1,0,0]
	v_cndmask_b32_e64 v142, v142, v146, s[4:5]
	v_mul_f32_e32 v146, 0x4b800000, v159
	v_cmp_gt_f32_e32 vcc, s94, v159
	s_waitcnt lgkmcnt(0)
	s_nop 1
	v_add_f32_dpp v152, v152, v152 quad_perm:[2,3,0,1] row_mask:0xf bank_mask:0xf
	v_add_f32_dpp v153, v153, v153 quad_perm:[2,3,0,1] row_mask:0xf bank_mask:0xf
	v_cndmask_b32_e32 v146, v159, v146, vcc
	v_rsq_f32_e32 v146, v146
	v_mul_f32_e32 v159, 0x4b800000, v158
	v_cmp_gt_f32_e64 s[4:5], s94, v158
	v_pk_fma_f32 v[68:69], v[68:69], v[136:137], v[110:111] op_sel_hi:[1,0,1] neg_lo:[0,0,1] neg_hi:[0,0,1]
	v_pk_fma_f32 v[54:55], v[54:55], v[132:133], v[116:117] op_sel_hi:[1,0,1] neg_lo:[0,0,1] neg_hi:[0,0,1]
	v_cndmask_b32_e64 v158, v158, v159, s[4:5]
	v_pk_mul_f32 v[124:125], v[68:69], v[68:69]
	v_pk_mul_f32 v[126:127], v[54:55], v[54:55]
	v_pk_fma_f32 v[22:23], v[22:23], v[132:133], v[188:189] op_sel_hi:[1,0,1] neg_lo:[0,0,1] neg_hi:[0,0,1]
	v_rsq_f32_e32 v160, v158
	s_waitcnt lgkmcnt(0)
	s_nop 1
	v_add_f32_dpp v152, v152, v152 row_half_mirror row_mask:0xf bank_mask:0xf
	v_add_f32_dpp v153, v153, v153 row_half_mirror row_mask:0xf bank_mask:0xf
	v_mul_f32_e32 v158, 0x45800000, v146
	v_pk_mul_f32 v[136:137], v[36:37], v[36:37]
	v_pk_mul_f32 v[140:141], v[22:23], v[22:23]
	v_cndmask_b32_e32 v146, v146, v158, vcc
	v_mov_b32_e32 v158, v126
	v_mov_b32_e32 v159, v124
	v_mov_b32_e32 v124, v127
	v_pk_add_f32 v[124:125], v[158:159], v[124:125]
	v_mov_b32_e32 v126, v140
	v_mov_b32_e32 v127, v136
	v_pk_add_f32 v[124:125], v[124:125], v[126:127]
	v_mov_b32_e32 v136, v141
	v_pk_add_f32 v[126:127], v[124:125], v[136:137]
	s_waitcnt lgkmcnt(0)
	s_nop 1
	v_add_f32_dpp v152, v152, v152 row_mirror row_mask:0xf bank_mask:0xf
	v_add_f32_dpp v153, v153, v153 row_mirror row_mask:0xf bank_mask:0xf
	ds_bpermute_b32 v157, v162, v153
	ds_bpermute_b32 v156, v162, v152
	v_mul_f32_e32 v161, 0x45800000, v160
	s_waitcnt lgkmcnt(2)
	s_nop 1
	v_add_f32_dpp v126, v126, v126 quad_perm:[1,0,3,2] row_mask:0xf bank_mask:0xf
	v_add_f32_dpp v127, v127, v127 quad_perm:[1,0,3,2] row_mask:0xf bank_mask:0xf
	s_waitcnt lgkmcnt(0)
	v_pk_add_f32 v[140:141], v[152:153], v[156:157]
	v_cndmask_b32_e64 v124, v160, v161, s[4:5]
	v_pk_fma_f32 v[140:141], v[140:141], s[50:51], v[46:47] op_sel_hi:[1,0,0]
	v_pk_mul_f32 v[116:117], v[70:71], v[70:71]
	v_mul_f32_e32 v125, 0x4b800000, v141
	v_cmp_gt_f32_e32 vcc, s94, v141
	s_waitcnt lgkmcnt(0)
	s_nop 1
	v_add_f32_dpp v126, v126, v126 quad_perm:[2,3,0,1] row_mask:0xf bank_mask:0xf
	v_add_f32_dpp v127, v127, v127 quad_perm:[2,3,0,1] row_mask:0xf bank_mask:0xf
	v_cndmask_b32_e32 v125, v141, v125, vcc
	v_rsq_f32_e32 v125, v125
	v_mul_f32_e32 v141, 0x4b800000, v140
	v_cmp_gt_f32_e64 s[4:5], s94, v140
	v_pk_mul_f32 v[118:119], v[56:57], v[56:57]
	v_pk_fma_f32 v[24:25], v[24:25], v[134:135], v[192:193] op_sel_hi:[1,0,1] neg_lo:[0,0,1] neg_hi:[0,0,1]
	v_cndmask_b32_e64 v140, v140, v141, s[4:5]
	v_rsq_f32_e32 v152, v140
	v_mul_f32_e32 v140, 0x45800000, v125
	v_pk_mul_f32 v[132:133], v[38:39], v[38:39]
	v_pk_mul_f32 v[134:135], v[24:25], v[24:25]
	v_cndmask_b32_e32 v125, v125, v140, vcc
	v_mov_b32_e32 v140, v118
	v_mov_b32_e32 v141, v116
	v_mov_b32_e32 v116, v119
	s_waitcnt lgkmcnt(0)
	s_nop 1
	v_add_f32_dpp v126, v126, v126 row_half_mirror row_mask:0xf bank_mask:0xf
	v_add_f32_dpp v127, v127, v127 row_half_mirror row_mask:0xf bank_mask:0xf
	v_pk_add_f32 v[116:117], v[140:141], v[116:117]
	v_mov_b32_e32 v118, v134
	v_mov_b32_e32 v119, v132
	v_pk_add_f32 v[116:117], v[116:117], v[118:119]
	v_mov_b32_e32 v132, v135
	v_pk_add_f32 v[118:119], v[116:117], v[132:133]
	s_waitcnt lgkmcnt(0)
	s_nop 1
	v_add_f32_dpp v126, v126, v126 row_mirror row_mask:0xf bank_mask:0xf
	v_add_f32_dpp v127, v127, v127 row_mirror row_mask:0xf bank_mask:0xf
	ds_bpermute_b32 v137, v162, v127
	ds_bpermute_b32 v136, v162, v126
	v_pk_mul_f32 v[108:109], v[72:73], v[72:73]
	s_waitcnt lgkmcnt(2)
	s_nop 1
	v_add_f32_dpp v118, v118, v118 quad_perm:[1,0,3,2] row_mask:0xf bank_mask:0xf
	v_add_f32_dpp v119, v119, v119 quad_perm:[1,0,3,2] row_mask:0xf bank_mask:0xf
	s_waitcnt lgkmcnt(0)
	v_pk_add_f32 v[126:127], v[126:127], v[136:137]
	v_pk_mul_f32 v[110:111], v[58:59], v[58:59]
	v_pk_fma_f32 v[126:127], v[126:127], s[50:51], v[46:47] op_sel_hi:[1,0,0]
	v_pk_fma_f32 v[40:41], v[40:41], v[130:131], v[194:195] op_sel_hi:[1,0,1] neg_lo:[0,0,1] neg_hi:[0,0,1]
	v_mul_f32_e32 v117, 0x4b800000, v127
	v_cmp_gt_f32_e32 vcc, s94, v127
	s_waitcnt lgkmcnt(0)
	s_nop 1
	v_add_f32_dpp v118, v118, v118 quad_perm:[2,3,0,1] row_mask:0xf bank_mask:0xf
	v_add_f32_dpp v119, v119, v119 quad_perm:[2,3,0,1] row_mask:0xf bank_mask:0xf
	v_cndmask_b32_e32 v117, v127, v117, vcc
	v_rsq_f32_e32 v117, v117
	v_pk_fma_f32 v[26:27], v[26:27], v[128:129], v[196:197] op_sel_hi:[1,0,1] neg_lo:[0,0,1] neg_hi:[0,0,1]
	v_pk_mul_f32 v[130:131], v[40:41], v[40:41]
	v_pk_mul_f32 v[128:129], v[26:27], v[26:27]
	s_waitcnt lgkmcnt(0)
	s_nop 1
	v_add_f32_dpp v118, v118, v118 row_half_mirror row_mask:0xf bank_mask:0xf
	v_add_f32_dpp v119, v119, v119 row_half_mirror row_mask:0xf bank_mask:0xf
	v_mul_f32_e32 v132, 0x45800000, v117
	v_cndmask_b32_e32 v117, v117, v132, vcc
	v_mov_b32_e32 v132, v110
	v_mov_b32_e32 v133, v108
	v_mov_b32_e32 v108, v111
	v_pk_add_f32 v[108:109], v[132:133], v[108:109]
	v_mov_b32_e32 v110, v128
	v_mov_b32_e32 v111, v130
	v_pk_add_f32 v[108:109], v[108:109], v[110:111]
	v_mov_b32_e32 v130, v129
	v_pk_add_f32 v[108:109], v[108:109], v[130:131]
	v_mul_f32_e32 v153, 0x45800000, v152
	v_cndmask_b32_e64 v116, v152, v153, s[4:5]
	v_mul_f32_e32 v127, 0x4b800000, v126
	v_cmp_gt_f32_e64 s[4:5], s94, v126
	s_waitcnt lgkmcnt(0)
	s_nop 1
	v_add_f32_dpp v108, v108, v108 quad_perm:[1,0,3,2] row_mask:0xf bank_mask:0xf
	v_add_f32_dpp v109, v109, v109 quad_perm:[1,0,3,2] row_mask:0xf bank_mask:0xf
	v_cndmask_b32_e64 v126, v126, v127, s[4:5]
	v_rsq_f32_e32 v134, v126
	v_mul_f32_e32 v135, 0x45800000, v134
	v_cndmask_b32_e64 v128, v134, v135, s[4:5]
	v_pk_mul_f32 v[104:105], v[74:75], v[74:75]
	s_waitcnt lgkmcnt(0)
	s_nop 1
	v_add_f32_dpp v118, v118, v118 row_mirror row_mask:0xf bank_mask:0xf
	v_add_f32_dpp v119, v119, v119 row_mirror row_mask:0xf bank_mask:0xf
	s_waitcnt lgkmcnt(0)
	s_nop 1
	v_add_f32_dpp v108, v108, v108 quad_perm:[2,3,0,1] row_mask:0xf bank_mask:0xf
	v_add_f32_dpp v109, v109, v109 quad_perm:[2,3,0,1] row_mask:0xf bank_mask:0xf
	ds_bpermute_b32 v127, v162, v119
	ds_bpermute_b32 v126, v162, v118
	v_pk_mul_f32 v[106:107], v[60:61], v[60:61]
	v_pk_fma_f32 v[42:43], v[42:43], v[122:123], v[198:199] op_sel_hi:[1,0,1] neg_lo:[0,0,1] neg_hi:[0,0,1]
	s_waitcnt lgkmcnt(0)
	v_pk_add_f32 v[118:119], v[118:119], v[126:127]
	v_pk_fma_f32 v[28:29], v[28:29], v[120:121], v[200:201] op_sel_hi:[1,0,1] neg_lo:[0,0,1] neg_hi:[0,0,1]
	s_waitcnt lgkmcnt(0)
	s_nop 1
	v_add_f32_dpp v108, v108, v108 row_half_mirror row_mask:0xf bank_mask:0xf
	v_add_f32_dpp v109, v109, v109 row_half_mirror row_mask:0xf bank_mask:0xf
	v_pk_fma_f32 v[118:119], v[118:119], s[50:51], v[46:47] op_sel_hi:[1,0,0]
	v_mul_f32_e32 v126, 0x4b800000, v119
	v_cmp_gt_f32_e32 vcc, s94, v119
	v_cmp_gt_f32_e64 s[4:5], s94, v118
	v_pk_mul_f32 v[122:123], v[42:43], v[42:43]
	v_cndmask_b32_e32 v119, v119, v126, vcc
	v_rsq_f32_e32 v119, v119
	v_mul_f32_e32 v126, 0x4b800000, v118
	s_waitcnt lgkmcnt(0)
	s_nop 1
	v_add_f32_dpp v108, v108, v108 row_mirror row_mask:0xf bank_mask:0xf
	v_add_f32_dpp v109, v109, v109 row_mirror row_mask:0xf bank_mask:0xf
	v_cndmask_b32_e64 v118, v118, v126, s[4:5]
	ds_bpermute_b32 v111, v162, v109
	ds_bpermute_b32 v110, v162, v108
	v_rsq_f32_e32 v126, v118
	v_mul_f32_e32 v118, 0x45800000, v119
	v_cndmask_b32_e32 v118, v119, v118, vcc
	v_pk_mul_f32 v[120:121], v[28:29], v[28:29]
	v_mul_f32_e32 v127, 0x3f4ccccd, v118
	v_mov_b32_e32 v118, v106
	v_mov_b32_e32 v119, v104
	v_mov_b32_e32 v104, v107
	v_pk_add_f32 v[104:105], v[118:119], v[104:105]
	v_mov_b32_e32 v106, v120
	v_mov_b32_e32 v107, v122
	v_pk_add_f32 v[104:105], v[104:105], v[106:107]
	v_mov_b32_e32 v122, v121
	s_waitcnt lgkmcnt(0)
	v_pk_add_f32 v[108:109], v[108:109], v[110:111]
	v_pk_add_f32 v[104:105], v[104:105], v[122:123]
	v_pk_fma_f32 v[108:109], v[108:109], s[50:51], v[46:47] op_sel_hi:[1,0,0]
	v_mul_f32_e32 v110, 0x4b800000, v109
	v_cmp_gt_f32_e32 vcc, s94, v109
	v_mul_f32_e32 v129, 0x45800000, v126
	v_cndmask_b32_e64 v118, v126, v129, s[4:5]
	v_cndmask_b32_e32 v109, v109, v110, vcc
	v_rsq_f32_e32 v109, v109
	s_waitcnt lgkmcnt(0)
	s_nop 1
	v_add_f32_dpp v104, v104, v104 quad_perm:[1,0,3,2] row_mask:0xf bank_mask:0xf
	v_add_f32_dpp v105, v105, v105 quad_perm:[1,0,3,2] row_mask:0xf bank_mask:0xf
	v_mul_f32_e32 v111, 0x3f4ccccd, v118
	v_mul_f32_e32 v118, 0x45800000, v109
	v_cndmask_b32_e32 v109, v109, v118, vcc
	v_mul_f32_e32 v118, 0x3f4ccccd, v109
	v_mul_f32_e32 v109, 0x4b800000, v108
	v_cmp_gt_f32_e32 vcc, s94, v108
	v_pk_mul_f32 v[100:101], v[76:77], v[76:77]
	v_pk_mul_f32 v[102:103], v[62:63], v[62:63]
	v_pk_fma_f32 v[44:45], v[44:45], v[112:113], v[202:203] op_sel_hi:[1,0,1] neg_lo:[0,0,1] neg_hi:[0,0,1]
	v_cndmask_b32_e32 v108, v108, v109, vcc
	v_pk_mul_f32 v[112:113], v[44:45], v[44:45]
	v_pk_mul_f32 v[114:115], v[30:31], v[30:31]
	v_rsq_f32_e32 v119, v108
	v_mov_b32_e32 v108, v102
	v_mov_b32_e32 v109, v100
	v_mov_b32_e32 v100, v103
	s_waitcnt lgkmcnt(0)
	s_nop 1
	v_add_f32_dpp v104, v104, v104 quad_perm:[2,3,0,1] row_mask:0xf bank_mask:0xf
	v_add_f32_dpp v105, v105, v105 quad_perm:[2,3,0,1] row_mask:0xf bank_mask:0xf
	v_pk_add_f32 v[100:101], v[108:109], v[100:101]
	v_mov_b32_e32 v102, v114
	v_mov_b32_e32 v103, v112
	v_pk_add_f32 v[100:101], v[100:101], v[102:103]
	v_mov_b32_e32 v112, v115
	v_pk_add_f32 v[100:101], v[100:101], v[112:113]
	s_waitcnt lgkmcnt(0)
	s_nop 1
	v_add_f32_dpp v104, v104, v104 row_half_mirror row_mask:0xf bank_mask:0xf
	v_add_f32_dpp v105, v105, v105 row_half_mirror row_mask:0xf bank_mask:0xf
	v_mul_f32_e32 v108, 0x45800000, v119
	s_waitcnt lgkmcnt(0)
	s_nop 1
	v_add_f32_dpp v100, v100, v100 quad_perm:[1,0,3,2] row_mask:0xf bank_mask:0xf
	v_add_f32_dpp v101, v101, v101 quad_perm:[1,0,3,2] row_mask:0xf bank_mask:0xf
	s_waitcnt lgkmcnt(0)
	s_nop 1
	v_add_f32_dpp v104, v104, v104 row_mirror row_mask:0xf bank_mask:0xf
	v_add_f32_dpp v105, v105, v105 row_mirror row_mask:0xf bank_mask:0xf
	ds_bpermute_b32 v107, v162, v105
	ds_bpermute_b32 v106, v162, v104
	global_load_dword v110, v167, s[8:9]
	s_waitcnt lgkmcnt(2)
	s_nop 1
	v_add_f32_dpp v100, v100, v100 quad_perm:[2,3,0,1] row_mask:0xf bank_mask:0xf
	v_add_f32_dpp v101, v101, v101 quad_perm:[2,3,0,1] row_mask:0xf bank_mask:0xf
	s_waitcnt lgkmcnt(0)
	v_pk_add_f32 v[104:105], v[104:105], v[106:107]
	global_load_dword v106, v167, s[8:9] offset:128
	v_pk_fma_f32 v[104:105], v[104:105], s[50:51], v[46:47] op_sel_hi:[1,0,0]
	v_mul_f32_e32 v142, 0x3f4ccccd, v142
	v_mul_f32_e32 v107, 0x4b800000, v105
	v_cmp_gt_f32_e64 s[4:5], s94, v105
	s_waitcnt lgkmcnt(0)
	s_nop 1
	v_add_f32_dpp v100, v100, v100 row_half_mirror row_mask:0xf bank_mask:0xf
	v_add_f32_dpp v101, v101, v101 row_half_mirror row_mask:0xf bank_mask:0xf
	v_cndmask_b32_e64 v105, v105, v107, s[4:5]
	v_rsq_f32_e32 v105, v105
	v_cndmask_b32_e32 v107, v119, v108, vcc
	v_cmp_gt_f32_e32 vcc, s94, v104
	v_mul_f32_e32 v48, v48, v142
	v_mul_f32_e32 v108, 0x45800000, v105
	s_waitcnt lgkmcnt(0)
	s_nop 1
	v_add_f32_dpp v100, v100, v100 row_mirror row_mask:0xf bank_mask:0xf
	v_add_f32_dpp v101, v101, v101 row_mirror row_mask:0xf bank_mask:0xf
	v_cndmask_b32_e64 v105, v105, v108, s[4:5]
	v_mul_f32_e32 v108, 0x4b800000, v104
	ds_bpermute_b32 v103, v162, v101
	ds_bpermute_b32 v102, v162, v100
	v_cndmask_b32_e32 v104, v104, v108, vcc
	v_rsq_f32_e32 v104, v104
	v_mul_f32_e32 v49, v49, v142
	v_mul_f32_e32 v146, 0x3f4ccccd, v146
	s_waitcnt lgkmcnt(0)
	v_pk_add_f32 v[100:101], v[100:101], v[102:103]
	v_mul_f32_e32 v108, 0x45800000, v104
	v_pk_fma_f32 v[46:47], v[100:101], s[50:51], v[46:47] op_sel_hi:[1,0,0]
	v_cndmask_b32_e32 v104, v104, v108, vcc
	v_mul_f32_e32 v100, 0x4b800000, v47
	v_cmp_gt_f32_e32 vcc, s94, v47
	v_cmp_gt_f32_e64 s[4:5], s94, v46
	v_mul_f32_e32 v64, v64, v146
	v_cndmask_b32_e32 v47, v47, v100, vcc
	v_mul_f32_e32 v100, 0x4b800000, v46
	v_rsq_f32_e32 v47, v47
	v_cndmask_b32_e64 v46, v46, v100, s[4:5]
	v_rsq_f32_e32 v46, v46
	v_mul_f32_e32 v16, v16, v142
	v_mul_f32_e32 v100, 0x45800000, v47
	v_cndmask_b32_e32 v47, v47, v100, vcc
	v_mul_f32_e32 v100, 0x45800000, v46
	v_cndmask_b32_e64 v46, v46, v100, s[4:5]
	global_load_dword v100, v167, s[8:9] offset:256
	global_load_dword v101, v167, s[8:9] offset:384
	v_mul_f32_e32 v17, v17, v142
	v_mul_f32_e32 v124, 0x3f4ccccd, v124
	v_mul_f32_e32 v50, v50, v124
	v_mul_f32_e32 v32, v32, v146
	v_mul_f32_e32 v125, 0x3f4ccccd, v125
	v_mul_f32_e32 v66, v66, v125
	v_mul_f32_e32 v18, v18, v124
	v_mul_f32_e32 v116, 0x3f4ccccd, v116
	v_mul_f32_e32 v52, v52, v116
	v_mul_f32_e32 v34, v34, v125
	v_mul_f32_e32 v117, 0x3f4ccccd, v117
	v_mul_f32_e32 v68, v68, v117
	v_mul_f32_e32 v20, v20, v116
	v_mul_f32_e32 v128, 0x3f4ccccd, v128
	v_mul_f32_e32 v54, v54, v128
	v_mul_f32_e32 v36, v36, v117
	v_mul_f32_e32 v70, v70, v127
	v_mul_f32_e32 v22, v22, v128
	v_mul_f32_e32 v56, v56, v111
	v_mul_f32_e32 v38, v38, v127
	v_mul_f32_e32 v72, v72, v118
	v_mul_f32_e32 v24, v24, v111
	v_mul_f32_e32 v107, 0x3f4ccccd, v107
	v_mul_f32_e32 v58, v58, v107
	v_mul_f32_e32 v40, v40, v118
	v_mul_f32_e32 v105, 0x3f4ccccd, v105
	v_mul_f32_e32 v74, v74, v105
	v_mul_f32_e32 v26, v26, v107
	v_mul_f32_e32 v104, 0x3f4ccccd, v104
	v_mul_f32_e32 v60, v60, v104
	v_mul_f32_e32 v42, v42, v105
	v_mul_f32_e32 v47, 0x3f4ccccd, v47
	v_mul_f32_e32 v76, v76, v47
	s_waitcnt vmcnt(3)
	v_mul_f32_e32 v48, v48, v110
	v_mul_f32_e32 v64, v64, v110
	v_mul_f32_e32 v50, v50, v110
	v_mul_f32_e32 v66, v66, v110
	v_mul_f32_e32 v52, v52, v110
	s_waitcnt vmcnt(2)
	v_mul_f32_e32 v49, v49, v106
	ds_write2_b32 v166, v48, v49 offset0:128 offset1:160
	v_mul_f32_e32 v48, v65, v146
	v_mul_f32_e32 v48, v48, v106
	ds_write2_b32 v168, v64, v48 offset1:32
	v_mul_f32_e32 v48, v51, v124
	v_mul_f32_e32 v48, v48, v106
	ds_write2_b32 v168, v50, v48 offset0:128 offset1:160
	v_mul_f32_e32 v48, v67, v125
	v_mul_f32_e32 v48, v48, v106
	ds_write2_b32 v169, v66, v48 offset1:32
	v_mul_f32_e32 v48, v53, v116
	v_mul_f32_e32 v48, v48, v106
	ds_write2_b32 v169, v52, v48 offset0:128 offset1:160
	v_mul_f32_e32 v48, v69, v117
	v_mul_f32_e32 v68, v68, v110
	v_mul_f32_e32 v48, v48, v106
	ds_write2_b32 v170, v68, v48 offset1:32
	v_mul_f32_e32 v48, v55, v128
	v_mul_f32_e32 v54, v54, v110
	v_mul_f32_e32 v48, v48, v106
	ds_write2_b32 v170, v54, v48 offset0:128 offset1:160
	v_mul_f32_e32 v48, v71, v127
	v_mul_f32_e32 v70, v70, v110
	v_mul_f32_e32 v48, v48, v106
	ds_write2_b32 v171, v70, v48 offset1:32
	v_mul_f32_e32 v48, v57, v111
	v_mul_f32_e32 v56, v56, v110
	v_mul_f32_e32 v48, v48, v106
	ds_write2_b32 v171, v56, v48 offset0:128 offset1:160
	v_mul_f32_e32 v48, v73, v118
	v_mul_f32_e32 v72, v72, v110
	v_mul_f32_e32 v48, v48, v106
	ds_write2_b32 v172, v72, v48 offset1:32
	v_mul_f32_e32 v48, v59, v107
	v_mul_f32_e32 v58, v58, v110
	v_mul_f32_e32 v48, v48, v106
	ds_write2_b32 v172, v58, v48 offset0:128 offset1:160
	v_mul_f32_e32 v48, v75, v105
	v_mul_f32_e32 v74, v74, v110
	s_waitcnt vmcnt(1)
	v_mul_f32_e32 v16, v16, v100
	s_waitcnt vmcnt(0)
	v_mul_f32_e32 v17, v17, v101
	ds_write2_b32 v166, v16, v17 offset0:192 offset1:224
	v_mul_f32_e32 v16, v33, v146
	v_mul_f32_e32 v32, v32, v100
	v_mul_f32_e32 v16, v16, v101
	ds_write2_b32 v168, v32, v16 offset0:64 offset1:96
	v_mul_f32_e32 v16, v19, v124
	v_mul_f32_e32 v18, v18, v100
	v_mul_f32_e32 v16, v16, v101
	ds_write2_b32 v168, v18, v16 offset0:192 offset1:224
	v_mul_f32_e32 v16, v35, v125
	v_mul_f32_e32 v34, v34, v100
	v_mul_f32_e32 v16, v16, v101
	ds_write2_b32 v169, v34, v16 offset0:64 offset1:96
	v_mul_f32_e32 v16, v21, v116
	v_mul_f32_e32 v20, v20, v100
	v_mul_f32_e32 v16, v16, v101
	ds_write2_b32 v169, v20, v16 offset0:192 offset1:224
	v_mul_f32_e32 v16, v37, v117
	v_mul_f32_e32 v36, v36, v100
	v_mul_f32_e32 v16, v16, v101
	ds_write2_b32 v170, v36, v16 offset0:64 offset1:96
	v_mul_f32_e32 v16, v23, v128
	v_mul_f32_e32 v22, v22, v100
	v_mul_f32_e32 v16, v16, v101
	ds_write2_b32 v170, v22, v16 offset0:192 offset1:224
	v_mul_f32_e32 v16, v39, v127
	v_mul_f32_e32 v38, v38, v100
	v_mul_f32_e32 v16, v16, v101
	ds_write2_b32 v171, v38, v16 offset0:64 offset1:96
	v_mul_f32_e32 v16, v25, v111
	v_mul_f32_e32 v24, v24, v100
	v_mul_f32_e32 v16, v16, v101
	ds_write2_b32 v171, v24, v16 offset0:192 offset1:224
	v_mul_f32_e32 v16, v41, v118
	v_mul_f32_e32 v40, v40, v100
	v_mul_f32_e32 v16, v16, v101
	ds_write2_b32 v172, v40, v16 offset0:64 offset1:96
	v_mul_f32_e32 v16, v27, v107
	v_mul_f32_e32 v48, v48, v106
	v_mul_f32_e32 v26, v26, v100
	v_mul_f32_e32 v16, v16, v101
	ds_write2_b32 v173, v74, v48 offset1:32
	v_mul_f32_e32 v48, v61, v104
	ds_write2_b32 v172, v26, v16 offset0:192 offset1:224
	v_mul_f32_e32 v16, v43, v105
	v_mul_f32_e32 v60, v110, v60
	v_mul_f32_e32 v48, v48, v106
	v_mul_f32_e32 v42, v42, v100
	v_mul_f32_e32 v16, v16, v101
	ds_write2_b32 v173, v60, v48 offset0:128 offset1:160
	v_mul_f32_e32 v48, v77, v47
	v_mul_f32_e32 v28, v28, v104
	ds_write2_b32 v173, v42, v16 offset0:64 offset1:96
	v_mul_f32_e32 v16, v29, v104
	v_mul_f32_e32 v46, 0x3f4ccccd, v46
	v_mul_f32_e32 v76, v110, v76
	v_mul_f32_e32 v48, v48, v106
	v_mul_f32_e32 v28, v28, v100
	v_mul_f32_e32 v16, v16, v101
	v_mul_f32_e32 v62, v62, v46
	ds_write2_b32 v174, v76, v48 offset1:32
	v_mul_f32_e32 v48, v63, v46
	v_mul_f32_e32 v44, v44, v47
	ds_write2_b32 v173, v28, v16 offset0:192 offset1:224
	v_mul_f32_e32 v16, v45, v47
	v_mul_f32_e32 v138, 0x3f4ccccd, v138
	v_mul_f32_e32 v62, v110, v62
	v_mul_f32_e32 v48, v48, v106
	v_mul_f32_e32 v44, v44, v100
	v_mul_f32_e32 v16, v16, v101
	v_mul_f32_e32 v98, v98, v138
	v_mul_f32_e32 v99, v99, v138
	ds_write2_b32 v174, v62, v48 offset0:128 offset1:160
	v_mul_f32_e32 v48, v78, v138
	v_mul_f32_e32 v30, v30, v46
	v_mul_f32_e32 v49, v79, v138
	ds_write2_b32 v174, v44, v16 offset0:64 offset1:96
	v_mul_f32_e32 v16, v31, v46
	v_mul_f32_e32 v98, v98, v110
	v_mul_f32_e32 v99, v99, v106
	v_mul_f32_e32 v48, v48, v100
	v_mul_f32_e32 v30, v30, v100
	v_mul_f32_e32 v49, v49, v101
	v_mul_f32_e32 v16, v16, v101
	ds_write2_b32 v166, v98, v99 offset1:32
	ds_write2_b32 v166, v48, v49 offset0:64 offset1:96
	ds_write2_b32 v174, v30, v16 offset0:192 offset1:224
